# dn_chunk_pre: batched LDS reads of the 16 exec-masked M-tile scaling blocks (one wait instead of 16)
# baseline (speedup 1.0000x reference)
.LBB0_432:
	s_and_saveexec_b64 s[4:5], s[42:43]
	s_cbranch_execz .LBB0_466
	ds_read_b128 v[0:3], v52
	ds_read_b128 v[4:7], v53
	ds_read_b128 v[112:115], v52 offset:32
	ds_read_b128 v[116:119], v53 offset:32
	ds_read_b128 v[120:123], v52 offset:64
	ds_read_b128 v[124:127], v53 offset:64
	ds_read_b128 v[130:133], v52 offset:96
	ds_read_b128 v[134:137], v53 offset:96
	ds_read_b32 v111, v55 offset:51200
	s_waitcnt lgkmcnt(7)
	v_mfma_f32_32x32x16_bf16 v[0:15], v[0:3], v[4:7], 0
	s_waitcnt lgkmcnt(5)
	v_mfma_f32_32x32x16_bf16 v[0:15], v[112:115], v[116:119], v[0:15]
	s_waitcnt lgkmcnt(3)
	v_mfma_f32_32x32x16_bf16 v[0:15], v[120:123], v[124:127], v[0:15]
	s_waitcnt lgkmcnt(1)
	v_mfma_f32_32x32x16_bf16 v[0:15], v[130:133], v[134:137], v[0:15]
	ds_read_b128 v[112:115], v52 offset:128
	ds_read_b128 v[120:123], v53 offset:128
	ds_read_b128 v[116:119], v52 offset:160
	ds_read_b128 v[124:127], v53 offset:160
	ds_read_b128 v[130:133], v52 offset:192
	ds_read_b128 v[134:137], v53 offset:192
	ds_read_b128 v[138:141], v52 offset:224
	ds_read_b128 v[142:145], v53 offset:224
	s_waitcnt lgkmcnt(6)
	v_mfma_f32_32x32x16_bf16 v[0:15], v[112:115], v[120:123], v[0:15]
	v_mov_b32_e32 v112, 0
	v_mov_b32_e32 v113, 0
	s_waitcnt lgkmcnt(4)
	v_mfma_f32_32x32x16_bf16 v[0:15], v[116:119], v[124:127], v[0:15]
	s_waitcnt lgkmcnt(2)
	v_mfma_f32_32x32x16_bf16 v[0:15], v[130:133], v[134:137], v[0:15]
	s_waitcnt lgkmcnt(0)
	v_mfma_f32_32x32x16_bf16 v[0:15], v[138:141], v[142:145], v[0:15]
	ds_read2st64_b32 v[218:219], v58 offset0:200 offset1:201
	v_add_u32_e32 v220, 4, v58
	ds_read2st64_b32 v[220:221], v220 offset0:200 offset1:201
	v_add_u32_e32 v222, 8, v58
	ds_read2st64_b32 v[222:223], v222 offset0:200 offset1:201
	v_add_u32_e32 v224, 12, v58
	ds_read2st64_b32 v[224:225], v224 offset0:200 offset1:201
	v_add_u32_e32 v226, 32, v58
	ds_read2st64_b32 v[226:227], v226 offset0:200 offset1:201
	v_add_u32_e32 v228, 36, v58
	ds_read2st64_b32 v[228:229], v228 offset0:200 offset1:201
	v_add_u32_e32 v230, 40, v58
	ds_read2st64_b32 v[230:231], v230 offset0:200 offset1:201
	v_add_u32_e32 v232, 44, v58
	ds_read2st64_b32 v[232:233], v232 offset0:200 offset1:201
	v_add_u32_e32 v234, 64, v58
	ds_read2st64_b32 v[234:235], v234 offset0:200 offset1:201
	v_add_u32_e32 v236, 0x44, v58
	ds_read2st64_b32 v[236:237], v236 offset0:200 offset1:201
	v_add_u32_e32 v238, 0x48, v58
	ds_read2st64_b32 v[238:239], v238 offset0:200 offset1:201
	v_add_u32_e32 v240, 0x4c, v58
	ds_read2st64_b32 v[240:241], v240 offset0:200 offset1:201
	v_add_u32_e32 v242, 0x60, v58
	ds_read2st64_b32 v[242:243], v242 offset0:200 offset1:201
	v_add_u32_e32 v244, 0x64, v58
	ds_read2st64_b32 v[244:245], v244 offset0:200 offset1:201
	v_add_u32_e32 v246, 0x68, v58
	ds_read2st64_b32 v[246:247], v246 offset0:200 offset1:201
	ds_read2st64_b32 v[248:249], v60 offset0:200 offset1:201
	v_add_u32_e32 v250, v55, v59
	s_waitcnt lgkmcnt(0)
	v_sub_f32_e32 v218, v218, v111
	v_mul_f32_e32 v218, 0x3fb8aa3b, v218
	v_exp_f32_e32 v218, v218
	v_sub_f32_e32 v220, v220, v111
	v_mul_f32_e32 v220, 0x3fb8aa3b, v220
	v_exp_f32_e32 v220, v220
	v_sub_f32_e32 v222, v222, v111
	v_mul_f32_e32 v222, 0x3fb8aa3b, v222
	v_exp_f32_e32 v222, v222
	v_sub_f32_e32 v224, v224, v111
	v_mul_f32_e32 v224, 0x3fb8aa3b, v224
	v_exp_f32_e32 v224, v224
	v_sub_f32_e32 v226, v226, v111
	v_mul_f32_e32 v226, 0x3fb8aa3b, v226
	v_exp_f32_e32 v226, v226
	v_sub_f32_e32 v228, v228, v111
	v_mul_f32_e32 v228, 0x3fb8aa3b, v228
	v_exp_f32_e32 v228, v228
	v_sub_f32_e32 v230, v230, v111
	v_mul_f32_e32 v230, 0x3fb8aa3b, v230
	v_exp_f32_e32 v230, v230
	v_sub_f32_e32 v232, v232, v111
	v_mul_f32_e32 v232, 0x3fb8aa3b, v232
	v_exp_f32_e32 v232, v232
	v_sub_f32_e32 v234, v234, v111
	v_mul_f32_e32 v234, 0x3fb8aa3b, v234
	v_exp_f32_e32 v234, v234
	v_sub_f32_e32 v236, v236, v111
	v_mul_f32_e32 v236, 0x3fb8aa3b, v236
	v_exp_f32_e32 v236, v236
	v_sub_f32_e32 v238, v238, v111
	v_mul_f32_e32 v238, 0x3fb8aa3b, v238
	v_exp_f32_e32 v238, v238
	v_sub_f32_e32 v240, v240, v111
	v_mul_f32_e32 v240, 0x3fb8aa3b, v240
	v_exp_f32_e32 v240, v240
	v_sub_f32_e32 v242, v242, v111
	v_mul_f32_e32 v242, 0x3fb8aa3b, v242
	v_exp_f32_e32 v242, v242
	v_sub_f32_e32 v244, v244, v111
	v_mul_f32_e32 v244, 0x3fb8aa3b, v244
	v_exp_f32_e32 v244, v244
	v_sub_f32_e32 v246, v246, v111
	v_mul_f32_e32 v246, 0x3fb8aa3b, v246
	v_exp_f32_e32 v246, v246
	v_sub_f32_e32 v248, v248, v111
	v_mul_f32_e32 v248, 0x3fb8aa3b, v248
	v_exp_f32_e32 v248, v248
	s_nop 0
	v_mul_f32_e32 v219, v0, v219
	v_mul_f32_e32 v221, v1, v221
	v_mul_f32_e32 v223, v2, v223
	v_mul_f32_e32 v225, v3, v225
	v_mul_f32_e32 v227, v4, v227
	v_mul_f32_e32 v229, v5, v229
	v_mul_f32_e32 v231, v6, v231
	v_mul_f32_e32 v233, v7, v233
	v_mul_f32_e32 v235, v8, v235
	v_mul_f32_e32 v237, v9, v237
	v_mul_f32_e32 v239, v10, v239
	v_mul_f32_e32 v241, v11, v241
	v_mul_f32_e32 v243, v12, v243
	v_mul_f32_e32 v245, v13, v245
	v_mul_f32_e32 v247, v14, v247
	v_mul_f32_e32 v249, v15, v249
	v_mul_f32_e32 v219, v219, v218
	v_mul_f32_e32 v221, v221, v220
	v_mul_f32_e32 v223, v223, v222
	v_mul_f32_e32 v225, v225, v224
	v_mul_f32_e32 v227, v227, v226
	v_mul_f32_e32 v229, v229, v228
	v_mul_f32_e32 v231, v231, v230
	v_mul_f32_e32 v233, v233, v232
	v_mul_f32_e32 v235, v235, v234
	v_mul_f32_e32 v237, v237, v236
	v_mul_f32_e32 v239, v239, v238
	v_mul_f32_e32 v241, v241, v240
	v_mul_f32_e32 v243, v243, v242
	v_mul_f32_e32 v245, v245, v244
	v_mul_f32_e32 v247, v247, v246
	v_mul_f32_e32 v249, v249, v248
	v_cndmask_b32_e64 v219, 0, v219, s[90:91]
	v_cndmask_b32_e64 v221, 0, v221, s[50:51]
	v_cndmask_b32_e64 v223, 0, v223, s[52:53]
	v_cndmask_b32_e64 v225, 0, v225, s[54:55]
	v_cndmask_b32_e64 v227, 0, v227, s[56:57]
	v_cndmask_b32_e64 v229, 0, v229, s[58:59]
	v_cndmask_b32_e64 v231, 0, v231, s[60:61]
	v_cndmask_b32_e64 v233, 0, v233, s[62:63]
	v_cndmask_b32_e64 v235, 0, v235, s[64:65]
	v_cndmask_b32_e64 v237, 0, v237, s[66:67]
	v_cndmask_b32_e64 v239, 0, v239, s[68:69]
	v_cndmask_b32_e64 v241, 0, v241, s[70:71]
	v_cndmask_b32_e64 v243, 0, v243, s[72:73]
	v_cndmask_b32_e64 v245, 0, v245, s[74:75]
	v_cndmask_b32_e64 v247, 0, v247, s[76:77]
	v_cndmask_b32_e64 v249, 0, v249, s[78:79]
	ds_write_b32 v250, v219 offset:34816
	ds_write_b32 v93, v221 offset:34816
	ds_write_b32 v94, v223 offset:34816
	ds_write_b32 v95, v225 offset:34816
	ds_write_b32 v96, v227 offset:34816
	ds_write_b32 v97, v229 offset:34816
	ds_write_b32 v98, v231 offset:34816
	ds_write_b32 v99, v233 offset:34816
	ds_write_b32 v100, v235 offset:34816
	ds_write_b32 v101, v237 offset:34816
	ds_write_b32 v102, v239 offset:34816
	ds_write_b32 v103, v241 offset:34816
	ds_write_b32 v104, v243 offset:34816
	ds_write_b32 v105, v245 offset:34816
	ds_write_b32 v106, v247 offset:34816
	ds_write_b32 v107, v249 offset:34816
